# q7 plus removal of the redundant third workgroup barrier of the P2 dequeue (slot rewrite is fenced by the loop-head barrier)
# baseline (speedup 1.0000x reference)
; __global__ void __launch_bounds__(512) hybrid_fwd(Params p) {
;     ...
;             __syncthreads();
;             if (C.tid == 0) s_unit = (int)atomicAdd(ctl + 64 * (1 + l), 1u);
;             __syncthreads();
;             const int u = s_unit;
;             __syncthreads();
;             if (u >= 1024 + 1024 + 512) break;
;             const int v2 = u - 512, grpq = v2 >> 7, rq = v2 & 127;
.LBB0_321:
	s_or_b64 exec, exec, s[40:41]
	s_waitcnt lgkmcnt(0)
	s_barrier
	ds_read_b32 v0, v193
	s_movk_i32 s19, 0x9ff
	s_mov_b64 s[40:41], -1
	s_waitcnt lgkmcnt(0)
	v_cmp_lt_i32_e32 vcc, s19, v0
	v_readfirstlane_b32 s74, v0
	s_cbranch_vccnz .LBB0_316
	s_cmp_lt_u32 s74, 1536
	s_cbranch_scc0 .Lq4_c
	s_lshr_b32 s19, s74, 7
	s_mul_i32 s20, s19, 11
	s_lshr_b32 s20, s20, 5
	s_mul_i32 s21, s20, 3
	s_sub_u32 s19, s19, s21
	s_and_b32 s22, s74, 127
	s_cmp_eq_u32 s19, 1
	s_cbranch_scc1 .Lq7_attn
	s_lshl_b32 s21, s20, 2
	s_add_u32 s21, s21, s19
	s_lshr_b32 s19, s22, 6
	s_add_u32 s21, s21, s19
	s_and_b32 s22, s22, 63
	s_lshl_b32 s21, s21, 7
	s_add_u32 s74, s21, s22
	s_add_u32 s74, s74, 512
	s_branch .Lq4_done
